# in-proj GEMM epilogue: the 8 per-row rms statistics loads issued together (one round trip instead of 8 dependent ones)
# speedup vs baseline: 1.0451x; 1.0139x over previous
;     __device__ __forceinline__ void operator()(const f32x4 (&acc)[2][2][4][2], const Unit& u, int wr, int wc, int fr, int fq) const {
;         const int row0 = u.pm * BM + wr * 64 + fr;
;         float rsv[2][4];
; #pragma unroll
;         for (int ai = 0; ai < 2; ++ai) {
; #pragma unroll
;             for (int m = 0; m < 4; ++m) {
;                 const int row = row0 + ai * HALF + m * 16;
;                 const f32x4 h0 = *((const f32x4*)(hss + (size_t)row * 16) + fq);
;                 float ss = (h0[0] + h0[1]) + (h0[2] + h0[3]);
;                 ss += __shfl_xor(ss, 16); ss += __shfl_xor(ss, 32);
;                 rsv[ai][m] = 1.0f / sqrtf(ss * (1.0f / 1024.0f) + 1e-6f);
;             }
;             asm volatile("" ::: "memory");
;         }
.LBB0_143:
	v_and_b32_e32 v148, 64, v216
	v_xor_b32_e32 v0, 16, v216
	v_add_u32_e32 v148, 64, v148
	v_cmp_lt_i32_e32 vcc, v0, v148
	v_lshl_add_u32 v160, s44, 8, v139
	v_ashrrev_i32_e32 v161, 31, v160
	v_cndmask_b32_e32 v0, v216, v0, vcc
	v_lshlrev_b32_e32 v173, 2, v0
	v_xor_b32_e32 v0, 32, v216
	v_cmp_lt_i32_e32 vcc, v0, v148
	v_lshlrev_b64 v[148:149], 6, v[160:161]
	v_lshl_add_u64 v[148:149], v[142:143], 0, v[148:149]
	v_lshlrev_b64 v[248:249], 6, v[160:161]
	v_lshl_add_u64 v[248:249], v[142:143], 0, v[248:249]
	global_load_dwordx4 v[222:225], v[248:249], off
	v_add_u32_e32 v248, 0x10, v160
	v_ashrrev_i32_e32 v249, 31, v248
	v_lshlrev_b64 v[248:249], 6, v[248:249]
	v_lshl_add_u64 v[248:249], v[142:143], 0, v[248:249]
	global_load_dwordx4 v[226:229], v[248:249], off
	v_add_u32_e32 v248, 0x20, v160
	v_ashrrev_i32_e32 v249, 31, v248
	v_lshlrev_b64 v[248:249], 6, v[248:249]
	v_lshl_add_u64 v[248:249], v[142:143], 0, v[248:249]
	global_load_dwordx4 v[230:233], v[248:249], off
	v_add_u32_e32 v248, 0x30, v160
	v_ashrrev_i32_e32 v249, 31, v248
	v_lshlrev_b64 v[248:249], 6, v[248:249]
	v_lshl_add_u64 v[248:249], v[142:143], 0, v[248:249]
	global_load_dwordx4 v[234:237], v[248:249], off
	v_add_u32_e32 v248, 0x80, v160
	v_ashrrev_i32_e32 v249, 31, v248
	v_lshlrev_b64 v[248:249], 6, v[248:249]
	v_lshl_add_u64 v[248:249], v[142:143], 0, v[248:249]
	global_load_dwordx4 v[238:241], v[248:249], off
	v_add_u32_e32 v248, 0x90, v160
	v_ashrrev_i32_e32 v249, 31, v248
	v_lshlrev_b64 v[248:249], 6, v[248:249]
	v_lshl_add_u64 v[248:249], v[142:143], 0, v[248:249]
	global_load_dwordx4 v[242:245], v[248:249], off
	v_add_u32_e32 v248, 0xa0, v160
	v_ashrrev_i32_e32 v249, 31, v248
	v_lshlrev_b64 v[248:249], 6, v[248:249]
	v_lshl_add_u64 v[248:249], v[142:143], 0, v[248:249]
	global_load_dwordx4 v[180:183], v[248:249], off
	v_add_u32_e32 v248, 0xb0, v160
	v_ashrrev_i32_e32 v249, 31, v248
	v_lshlrev_b64 v[248:249], 6, v[248:249]
	v_lshl_add_u64 v[248:249], v[142:143], 0, v[248:249]
	global_load_dwordx4 v[184:187], v[248:249], off
	s_waitcnt vmcnt(0)
	v_mov_b64_e32 v[148:149], v[222:223]
	v_mov_b64_e32 v[150:151], v[224:225]
	v_cndmask_b32_e32 v0, v216, v0, vcc
	v_lshlrev_b32_e32 v0, 2, v0
	v_or_b32_e32 v164, 16, v160
	v_ashrrev_i32_e32 v165, 31, v164
	v_or_b32_e32 v158, 32, v160
	v_ashrrev_i32_e32 v159, 31, v158
	v_or_b32_e32 v156, 48, v160
	v_ashrrev_i32_e32 v157, 31, v156
	v_add_u32_e32 v154, 0x80, v160
	v_ashrrev_i32_e32 v155, 31, v154
	s_cmp_gt_i32 s43, 15
	s_cselect_b64 s[8:9], -1, 0
	s_waitcnt lgkmcnt(0)
	v_add_f32_e32 v148, v148, v149
	v_add_f32_e32 v149, v150, v151
	v_add_f32_e32 v148, v148, v149
	ds_bpermute_b32 v149, v173, v148
	s_waitcnt lgkmcnt(0)
	v_add_f32_e32 v148, v148, v149
	ds_bpermute_b32 v149, v0, v148
	s_waitcnt lgkmcnt(0)
	v_add_f32_e32 v148, v148, v149
	v_fmamk_f32 v148, v148, 0x3a800000, v211
	v_cmp_gt_f32_e32 vcc, s55, v148
	v_mul_f32_e32 v149, 0x4f800000, v148
	s_nop 0
	v_cndmask_b32_e32 v148, v148, v149, vcc
	v_sqrt_f32_e32 v149, v148
	s_nop 0
	v_add_u32_e32 v150, -1, v149
	v_fma_f32 v151, -v150, v149, v148
	v_cmp_ge_f32_e64 s[0:1], 0, v151
	v_add_u32_e32 v151, 1, v149
	s_nop 0
	v_cndmask_b32_e64 v150, v149, v150, s[0:1]
	v_fma_f32 v149, -v151, v149, v148
	v_cmp_lt_f32_e64 s[0:1], 0, v149
	s_nop 1
	v_cndmask_b32_e64 v149, v150, v151, s[0:1]
	v_mul_f32_e32 v150, 0x37800000, v149
	v_cndmask_b32_e32 v149, v149, v150, vcc
	v_cmp_class_f32_e32 vcc, v148, v212
	s_nop 1
	v_cndmask_b32_e32 v148, v149, v148, vcc
	v_div_scale_f32 v149, s[0:1], v148, v148, 1.0
	v_rcp_f32_e32 v150, v149
	s_mov_b64 s[0:1], -1
	v_fma_f32 v151, -v149, v150, 1.0
	v_fmac_f32_e32 v150, v151, v150
	v_div_scale_f32 v151, vcc, 1.0, v148, 1.0
	v_mul_f32_e32 v152, v151, v150
	v_fma_f32 v153, -v149, v152, v151
	v_fmac_f32_e32 v152, v153, v150
	v_fma_f32 v149, -v149, v152, v151
	v_div_fmas_f32 v149, v149, v150, v152
	v_div_fixup_f32 v162, v149, v148, 1.0
	v_lshlrev_b64 v[148:149], 6, v[164:165]
	v_lshl_add_u64 v[148:149], v[142:143], 0, v[148:149]
	v_mov_b64_e32 v[148:149], v[226:227]
	v_mov_b64_e32 v[150:151], v[228:229]
	v_add_u32_e32 v152, 0x90, v160
	v_ashrrev_i32_e32 v153, 31, v152
	s_and_b64 vcc, exec, s[8:9]
	s_waitcnt lgkmcnt(0)
	v_add_f32_e32 v148, v148, v149
	v_add_f32_e32 v149, v150, v151
	v_add_f32_e32 v148, v148, v149
	ds_bpermute_b32 v149, v173, v148
	s_waitcnt lgkmcnt(0)
	v_add_f32_e32 v171, v148, v149
	v_lshlrev_b64 v[148:149], 6, v[158:159]
	v_lshl_add_u64 v[148:149], v[142:143], 0, v[148:149]
	v_mov_b64_e32 v[148:149], v[230:231]
	v_mov_b64_e32 v[150:151], v[232:233]
	ds_bpermute_b32 v172, v0, v171
	s_waitcnt lgkmcnt(0)
	v_add_f32_e32 v148, v148, v149
	v_add_f32_e32 v149, v150, v151
	v_add_f32_e32 v148, v148, v149
	ds_bpermute_b32 v149, v173, v148
	s_waitcnt lgkmcnt(0)
	v_add_f32_e32 v169, v148, v149
	v_lshlrev_b64 v[148:149], 6, v[156:157]
	v_lshl_add_u64 v[148:149], v[142:143], 0, v[148:149]
	v_mov_b64_e32 v[148:149], v[234:235]
	v_mov_b64_e32 v[150:151], v[236:237]
	ds_bpermute_b32 v170, v0, v169
	s_waitcnt lgkmcnt(0)
	v_add_f32_e32 v148, v148, v149
	v_add_f32_e32 v149, v150, v151
	v_add_f32_e32 v148, v148, v149
	ds_bpermute_b32 v149, v173, v148
	s_waitcnt lgkmcnt(0)
	v_add_f32_e32 v167, v148, v149
	v_lshlrev_b64 v[148:149], 6, v[154:155]
	v_lshl_add_u64 v[148:149], v[142:143], 0, v[148:149]
	v_mov_b64_e32 v[148:149], v[238:239]
	v_mov_b64_e32 v[150:151], v[240:241]
	ds_bpermute_b32 v168, v0, v167
	s_waitcnt lgkmcnt(0)
	v_add_f32_e32 v148, v148, v149
	v_add_f32_e32 v149, v150, v151
	v_add_f32_e32 v148, v148, v149
	ds_bpermute_b32 v149, v173, v148
	s_waitcnt lgkmcnt(0)
	v_add_f32_e32 v161, v148, v149
	v_lshlrev_b64 v[148:149], 6, v[152:153]
	v_lshl_add_u64 v[148:149], v[142:143], 0, v[148:149]
	v_mov_b64_e32 v[148:149], v[242:243]
	v_mov_b64_e32 v[150:151], v[244:245]
	ds_bpermute_b32 v165, v0, v161
	s_waitcnt lgkmcnt(0)
	v_add_f32_e32 v148, v148, v149
	v_add_f32_e32 v149, v150, v151
	v_add_f32_e32 v148, v148, v149
	ds_bpermute_b32 v149, v173, v148
	v_add_u32_e32 v150, 0xa0, v160
	v_ashrrev_i32_e32 v151, 31, v150
	s_waitcnt lgkmcnt(0)
	v_add_f32_e32 v155, v148, v149
	v_lshlrev_b64 v[148:149], 6, v[150:151]
	v_lshl_add_u64 v[148:149], v[142:143], 0, v[148:149]
	v_mov_b64_e32 v[174:175], v[180:181]
	v_mov_b64_e32 v[176:177], v[182:183]
	ds_bpermute_b32 v157, v0, v155
	s_waitcnt lgkmcnt(0)
	v_add_f32_e32 v148, v174, v175
	v_add_f32_e32 v149, v176, v177
	v_add_f32_e32 v148, v148, v149
	ds_bpermute_b32 v149, v173, v148
	s_waitcnt lgkmcnt(0)
	v_add_f32_e32 v151, v148, v149
	v_add_u32_e32 v148, 0xb0, v160
	v_ashrrev_i32_e32 v149, 31, v148
	v_lshlrev_b64 v[174:175], 6, v[148:149]
	v_lshl_add_u64 v[174:175], v[142:143], 0, v[174:175]
	v_mov_b64_e32 v[174:175], v[184:185]
	v_mov_b64_e32 v[176:177], v[186:187]
	ds_bpermute_b32 v153, v0, v151
	s_waitcnt lgkmcnt(0)
	v_add_f32_e32 v149, v174, v175
	v_add_f32_e32 v159, v176, v177
	v_add_f32_e32 v149, v149, v159
	ds_bpermute_b32 v159, v173, v149
	s_waitcnt lgkmcnt(0)
	v_add_f32_e32 v149, v149, v159
	ds_bpermute_b32 v159, v0, v149
	s_cbranch_vccz .LBB0_147
;     __device__ __forceinline__ void operator()(const f32x4 (&acc)[2][2][4][2], const Unit& u, int wr, int wc, int fr, int fq) const {
;     ...
;                 } else {
;                     const int c0 = wc * 32 + 8 * fq;
;                     if (c0 < 72) {
;                         *(f32x4*)(misc + (size_t)row * 80 + c0) = acc[ai][0][m][0] * rs;
;                         *(f32x4*)(misc + (size_t)row * 80 + c0 + 4) = acc[ai][0][m][1] * rs;
;                     }
	s_and_saveexec_b64 s[0:1], s[6:7]
	s_cbranch_execz .LBB0_146
	s_movk_i32 s17, 0x140
	v_pk_mul_f32 v[176:177], v[128:129], v[162:163] op_sel_hi:[1,0]
	v_pk_mul_f32 v[174:175], v[126:127], v[162:163] op_sel_hi:[1,0]
	v_mad_i64_i32 v[178:179], s[26:27], v160, s17, v[140:141]
	global_store_dwordx4 v[178:179], v[174:177], off
	s_nop 1
	v_pk_mul_f32 v[176:177], v[124:125], v[162:163] op_sel_hi:[1,0]
	v_pk_mul_f32 v[174:175], v[122:123], v[162:163] op_sel_hi:[1,0]
	global_store_dwordx4 v[178:179], v[174:177], off offset:16

;     __device__ __forceinline__ void operator()(const f32x4 (&acc)[2][2][4][2], const Unit& u, int wr, int wc, int fr, int fq) const {
;         const int row0 = u.pm * BM + wr * 64 + fr;
;         float rsv[2][4];
; #pragma unroll
;         for (int ai = 0; ai < 2; ++ai) {
; #pragma unroll
;             for (int m = 0; m < 4; ++m) {
;                 const int row = row0 + ai * HALF + m * 16;
;                 const f32x4 h0 = *((const f32x4*)(hss + (size_t)row * 16) + fq);
;                 float ss = (h0[0] + h0[1]) + (h0[2] + h0[3]);
;                 ss += __shfl_xor(ss, 16); ss += __shfl_xor(ss, 32);
;                 rsv[ai][m] = 1.0f / sqrtf(ss * (1.0f / 1024.0f) + 1e-6f);
;             }
;             asm volatile("" ::: "memory");
;         }
.LBB0_381:
	v_and_b32_e32 v148, 64, v216
	v_xor_b32_e32 v0, 16, v216
	v_add_u32_e32 v148, 64, v148
	v_cmp_lt_i32_e32 vcc, v0, v148
	v_lshl_add_u32 v160, s46, 8, v139
	v_ashrrev_i32_e32 v161, 31, v160
	v_cndmask_b32_e32 v0, v216, v0, vcc
	v_lshlrev_b32_e32 v173, 2, v0
	v_xor_b32_e32 v0, 32, v216
	v_cmp_lt_i32_e32 vcc, v0, v148
	v_lshlrev_b64 v[148:149], 6, v[160:161]
	v_lshl_add_u64 v[148:149], v[142:143], 0, v[148:149]
	v_lshlrev_b64 v[248:249], 6, v[160:161]
	v_lshl_add_u64 v[248:249], v[142:143], 0, v[248:249]
	global_load_dwordx4 v[222:225], v[248:249], off
	v_add_u32_e32 v248, 0x10, v160
	v_ashrrev_i32_e32 v249, 31, v248
	v_lshlrev_b64 v[248:249], 6, v[248:249]
	v_lshl_add_u64 v[248:249], v[142:143], 0, v[248:249]
	global_load_dwordx4 v[226:229], v[248:249], off
	v_add_u32_e32 v248, 0x20, v160
	v_ashrrev_i32_e32 v249, 31, v248
	v_lshlrev_b64 v[248:249], 6, v[248:249]
	v_lshl_add_u64 v[248:249], v[142:143], 0, v[248:249]
	global_load_dwordx4 v[230:233], v[248:249], off
	v_add_u32_e32 v248, 0x30, v160
	v_ashrrev_i32_e32 v249, 31, v248
	v_lshlrev_b64 v[248:249], 6, v[248:249]
	v_lshl_add_u64 v[248:249], v[142:143], 0, v[248:249]
	global_load_dwordx4 v[234:237], v[248:249], off
	v_add_u32_e32 v248, 0x80, v160
	v_ashrrev_i32_e32 v249, 31, v248
	v_lshlrev_b64 v[248:249], 6, v[248:249]
	v_lshl_add_u64 v[248:249], v[142:143], 0, v[248:249]
	global_load_dwordx4 v[238:241], v[248:249], off
	v_add_u32_e32 v248, 0x90, v160
	v_ashrrev_i32_e32 v249, 31, v248
	v_lshlrev_b64 v[248:249], 6, v[248:249]
	v_lshl_add_u64 v[248:249], v[142:143], 0, v[248:249]
	global_load_dwordx4 v[242:245], v[248:249], off
	v_add_u32_e32 v248, 0xa0, v160
	v_ashrrev_i32_e32 v249, 31, v248
	v_lshlrev_b64 v[248:249], 6, v[248:249]
	v_lshl_add_u64 v[248:249], v[142:143], 0, v[248:249]
	global_load_dwordx4 v[180:183], v[248:249], off
	v_add_u32_e32 v248, 0xb0, v160
	v_ashrrev_i32_e32 v249, 31, v248
	v_lshlrev_b64 v[248:249], 6, v[248:249]
	v_lshl_add_u64 v[248:249], v[142:143], 0, v[248:249]
	global_load_dwordx4 v[184:187], v[248:249], off
	s_waitcnt vmcnt(0)
	v_mov_b64_e32 v[148:149], v[222:223]
	v_mov_b64_e32 v[150:151], v[224:225]
	v_cndmask_b32_e32 v0, v216, v0, vcc
	v_lshlrev_b32_e32 v0, 2, v0
	v_or_b32_e32 v164, 16, v160
	v_ashrrev_i32_e32 v165, 31, v164
	v_or_b32_e32 v158, 32, v160
	v_ashrrev_i32_e32 v159, 31, v158
	v_or_b32_e32 v156, 48, v160
	v_ashrrev_i32_e32 v157, 31, v156
	v_add_u32_e32 v154, 0x80, v160
	v_ashrrev_i32_e32 v155, 31, v154
	s_cmp_gt_i32 s45, 15
	s_cselect_b64 s[8:9], -1, 0
	s_waitcnt lgkmcnt(0)
	v_add_f32_e32 v148, v148, v149
	v_add_f32_e32 v149, v150, v151
	v_add_f32_e32 v148, v148, v149
	ds_bpermute_b32 v149, v173, v148
	s_waitcnt lgkmcnt(0)
	v_add_f32_e32 v148, v148, v149
	ds_bpermute_b32 v149, v0, v148
	s_waitcnt lgkmcnt(0)
	v_add_f32_e32 v148, v148, v149
	v_fmamk_f32 v148, v148, 0x3a800000, v211
	v_cmp_gt_f32_e32 vcc, s55, v148
	v_mul_f32_e32 v149, 0x4f800000, v148
	s_nop 0
	v_cndmask_b32_e32 v148, v148, v149, vcc
	v_sqrt_f32_e32 v149, v148
	s_nop 0
	v_add_u32_e32 v150, -1, v149
	v_fma_f32 v151, -v150, v149, v148
	v_cmp_ge_f32_e64 s[0:1], 0, v151
	v_add_u32_e32 v151, 1, v149
	s_nop 0
	v_cndmask_b32_e64 v150, v149, v150, s[0:1]
	v_fma_f32 v149, -v151, v149, v148
	v_cmp_lt_f32_e64 s[0:1], 0, v149
	s_nop 1
	v_cndmask_b32_e64 v149, v150, v151, s[0:1]
	v_mul_f32_e32 v150, 0x37800000, v149
	v_cndmask_b32_e32 v149, v149, v150, vcc
	v_cmp_class_f32_e32 vcc, v148, v212
	s_nop 1
	v_cndmask_b32_e32 v148, v149, v148, vcc
	v_div_scale_f32 v149, s[0:1], v148, v148, 1.0
	v_rcp_f32_e32 v150, v149
	s_mov_b64 s[0:1], -1
	v_fma_f32 v151, -v149, v150, 1.0
	v_fmac_f32_e32 v150, v151, v150
	v_div_scale_f32 v151, vcc, 1.0, v148, 1.0
	v_mul_f32_e32 v152, v151, v150
	v_fma_f32 v153, -v149, v152, v151
	v_fmac_f32_e32 v152, v153, v150
	v_fma_f32 v149, -v149, v152, v151
	v_div_fmas_f32 v149, v149, v150, v152
	v_div_fixup_f32 v162, v149, v148, 1.0
	v_lshlrev_b64 v[148:149], 6, v[164:165]
	v_lshl_add_u64 v[148:149], v[142:143], 0, v[148:149]
	v_mov_b64_e32 v[148:149], v[226:227]
	v_mov_b64_e32 v[150:151], v[228:229]
	v_add_u32_e32 v152, 0x90, v160
	v_ashrrev_i32_e32 v153, 31, v152
	s_and_b64 vcc, exec, s[8:9]
	s_waitcnt lgkmcnt(0)
	v_add_f32_e32 v148, v148, v149
	v_add_f32_e32 v149, v150, v151
	v_add_f32_e32 v148, v148, v149
	ds_bpermute_b32 v149, v173, v148
	s_waitcnt lgkmcnt(0)
	v_add_f32_e32 v171, v148, v149
	v_lshlrev_b64 v[148:149], 6, v[158:159]
	v_lshl_add_u64 v[148:149], v[142:143], 0, v[148:149]
	v_mov_b64_e32 v[148:149], v[230:231]
	v_mov_b64_e32 v[150:151], v[232:233]
	ds_bpermute_b32 v172, v0, v171
	s_waitcnt lgkmcnt(0)
	v_add_f32_e32 v148, v148, v149
	v_add_f32_e32 v149, v150, v151
	v_add_f32_e32 v148, v148, v149
	ds_bpermute_b32 v149, v173, v148
	s_waitcnt lgkmcnt(0)
	v_add_f32_e32 v169, v148, v149
	v_lshlrev_b64 v[148:149], 6, v[156:157]
	v_lshl_add_u64 v[148:149], v[142:143], 0, v[148:149]
	v_mov_b64_e32 v[148:149], v[234:235]
	v_mov_b64_e32 v[150:151], v[236:237]
	ds_bpermute_b32 v170, v0, v169
	s_waitcnt lgkmcnt(0)
	v_add_f32_e32 v148, v148, v149
	v_add_f32_e32 v149, v150, v151
	v_add_f32_e32 v148, v148, v149
	ds_bpermute_b32 v149, v173, v148
	s_waitcnt lgkmcnt(0)
	v_add_f32_e32 v167, v148, v149
	v_lshlrev_b64 v[148:149], 6, v[154:155]
	v_lshl_add_u64 v[148:149], v[142:143], 0, v[148:149]
	v_mov_b64_e32 v[148:149], v[238:239]
	v_mov_b64_e32 v[150:151], v[240:241]
	ds_bpermute_b32 v168, v0, v167
	s_waitcnt lgkmcnt(0)
	v_add_f32_e32 v148, v148, v149
	v_add_f32_e32 v149, v150, v151
	v_add_f32_e32 v148, v148, v149
	ds_bpermute_b32 v149, v173, v148
	s_waitcnt lgkmcnt(0)
	v_add_f32_e32 v161, v148, v149
	v_lshlrev_b64 v[148:149], 6, v[152:153]
	v_lshl_add_u64 v[148:149], v[142:143], 0, v[148:149]
	v_mov_b64_e32 v[148:149], v[242:243]
	v_mov_b64_e32 v[150:151], v[244:245]
	ds_bpermute_b32 v165, v0, v161
	s_waitcnt lgkmcnt(0)
	v_add_f32_e32 v148, v148, v149
	v_add_f32_e32 v149, v150, v151
	v_add_f32_e32 v148, v148, v149
	ds_bpermute_b32 v149, v173, v148
	v_add_u32_e32 v150, 0xa0, v160
	v_ashrrev_i32_e32 v151, 31, v150
	s_waitcnt lgkmcnt(0)
	v_add_f32_e32 v155, v148, v149
	v_lshlrev_b64 v[148:149], 6, v[150:151]
	v_lshl_add_u64 v[148:149], v[142:143], 0, v[148:149]
	v_mov_b64_e32 v[174:175], v[180:181]
	v_mov_b64_e32 v[176:177], v[182:183]
	ds_bpermute_b32 v157, v0, v155
	s_waitcnt lgkmcnt(0)
	v_add_f32_e32 v148, v174, v175
	v_add_f32_e32 v149, v176, v177
	v_add_f32_e32 v148, v148, v149
	ds_bpermute_b32 v149, v173, v148
	s_waitcnt lgkmcnt(0)
	v_add_f32_e32 v151, v148, v149
	v_add_u32_e32 v148, 0xb0, v160
	v_ashrrev_i32_e32 v149, 31, v148
	v_lshlrev_b64 v[174:175], 6, v[148:149]
	v_lshl_add_u64 v[174:175], v[142:143], 0, v[174:175]
	v_mov_b64_e32 v[174:175], v[184:185]
	v_mov_b64_e32 v[176:177], v[186:187]
	ds_bpermute_b32 v153, v0, v151
	s_waitcnt lgkmcnt(0)
	v_add_f32_e32 v149, v174, v175
	v_add_f32_e32 v159, v176, v177
	v_add_f32_e32 v149, v149, v159
	ds_bpermute_b32 v159, v173, v149
	s_waitcnt lgkmcnt(0)
	v_add_f32_e32 v149, v149, v159
	ds_bpermute_b32 v159, v0, v149
	s_cbranch_vccz .LBB0_385
;     __device__ __forceinline__ void operator()(const f32x4 (&acc)[2][2][4][2], const Unit& u, int wr, int wc, int fr, int fq) const {
;     ...
;                 } else {
;                     const int c0 = wc * 32 + 8 * fq;
;                     if (c0 < 72) {
;                         *(f32x4*)(misc + (size_t)row * 80 + c0) = acc[ai][0][m][0] * rs;
;                         *(f32x4*)(misc + (size_t)row * 80 + c0 + 4) = acc[ai][0][m][1] * rs;
;                     }
	s_and_saveexec_b64 s[0:1], s[6:7]
	s_cbranch_execz .LBB0_384
	s_movk_i32 s19, 0x140
	v_pk_mul_f32 v[176:177], v[128:129], v[162:163] op_sel_hi:[1,0]
	v_pk_mul_f32 v[174:175], v[126:127], v[162:163] op_sel_hi:[1,0]
	v_mad_i64_i32 v[178:179], s[28:29], v160, s19, v[140:141]
	global_store_dwordx4 v[178:179], v[174:177], off
	s_nop 1
	v_pk_mul_f32 v[176:177], v[124:125], v[162:163] op_sel_hi:[1,0]
	v_pk_mul_f32 v[174:175], v[122:123], v[162:163] op_sel_hi:[1,0]
	global_store_dwordx4 v[178:179], v[174:177], off offset:16
